# hgrn k-tilde tile loop body rewritten: all LDS rows fetched in one batch (were 5 round trips per iteration)
# speedup vs baseline: 1.0129x; 1.0067x over previous
; #define LAS __attribute__((address_space(3)))
; __device__ __forceinline__ float fexp(float x) { return __expf(x); }
; __device__ __forceinline__ u32x4 pack8(const float (&f)[8]) { u32x4 w; w.x = pk2(f[0], f[1]); w.y = pk2(f[2], f[3]); w.z = pk2(f[4], f[5]); w.w = pk2(f[6], f[7]); return w; }
; __device__ __forceinline__ void hgrn_unit(const Ctx& X, LAS unsigned char* hl, int b, int c, int h, int tid_h, int w4, int lane, int layer) {
;     ...
;         for (int idx = lane; idx < nit; idx += 64) { const int j = idx >> 3, d8 = (idx & 7) * 8;
;             float kf[8]; unpack8(*(const LAS u32x4*)(Kt + j * LT + d8), kf);
;             float o[8];
; #pragma unroll
;             for (int e = 0; e < 8; ++e) o[e] = kf[e] * fexp(fminf(Gt[(16 * I) * 64 + d8 + e] - Gt[j * 64 + d8 + e], 80.f));
;             *(LAS u32x4*)(KI + j * LT + d8) = pack8(o); }
.LBB0_309:
	v_ashrrev_i32_e32 v22, 3, v17
	v_and_b32_e32 v23, 56, v16
	v_mul_lo_u32 v24, v22, s44
	v_lshlrev_b32_e32 v25, 1, v23
	v_add3_u32 v18, v33, v24, v25
	ds_read_b128 v[18:21], v18
	v_lshlrev_b32_e32 v36, 2, v23
	v_lshlrev_b32_e32 v37, 8, v22
	v_add_u32_e32 v23, v15, v36
	v_add3_u32 v22, v32, v37, v36
	ds_read_b128 v[134:137], v23
	ds_read_b128 v[138:141], v23 offset:16
	ds_read_b128 v[142:145], v22
	ds_read_b128 v[146:149], v22 offset:16
	v_add_u32_e32 v17, 64, v17
	v_cmp_le_i32_e32 vcc, s38, v17
	v_add_u32_e32 v16, 0x200, v16
	s_or_b64 s[6:7], vcc, s[6:7]
	s_waitcnt lgkmcnt(0)
	v_lshlrev_b32_e32 v26, 16, v18
	v_and_b32_e32 v27, 0xffff0000, v18
	v_lshlrev_b32_e32 v28, 16, v19
	v_and_b32_e32 v29, 0xffff0000, v19
	v_lshlrev_b32_e32 v30, 16, v20
	v_and_b32_e32 v31, 0xffff0000, v20
	v_lshlrev_b32_e32 v34, 16, v21
	v_and_b32_e32 v35, 0xffff0000, v21
	v_sub_f32_e32 v134, v134, v142
	v_sub_f32_e32 v135, v135, v143
	v_sub_f32_e32 v136, v136, v144
	v_sub_f32_e32 v137, v137, v145
	v_sub_f32_e32 v138, v138, v146
	v_sub_f32_e32 v139, v139, v147
	v_sub_f32_e32 v140, v140, v148
	v_sub_f32_e32 v141, v141, v149
	v_min_f32_e32 v134, 0x42a00000, v134
	v_min_f32_e32 v135, 0x42a00000, v135
	v_min_f32_e32 v136, 0x42a00000, v136
	v_min_f32_e32 v137, 0x42a00000, v137
	v_min_f32_e32 v138, 0x42a00000, v138
	v_min_f32_e32 v139, 0x42a00000, v139
	v_min_f32_e32 v140, 0x42a00000, v140
	v_min_f32_e32 v141, 0x42a00000, v141
	v_mul_f32_e32 v134, 0x3fb8aa3b, v134
	v_mul_f32_e32 v135, 0x3fb8aa3b, v135
	v_mul_f32_e32 v136, 0x3fb8aa3b, v136
	v_mul_f32_e32 v137, 0x3fb8aa3b, v137
	v_mul_f32_e32 v138, 0x3fb8aa3b, v138
	v_mul_f32_e32 v139, 0x3fb8aa3b, v139
	v_mul_f32_e32 v140, 0x3fb8aa3b, v140
	v_mul_f32_e32 v141, 0x3fb8aa3b, v141
	v_exp_f32_e32 v134, v134
	v_exp_f32_e32 v135, v135
	v_exp_f32_e32 v136, v136
	v_exp_f32_e32 v137, v137
	v_exp_f32_e32 v138, v138
	v_exp_f32_e32 v139, v139
	v_exp_f32_e32 v140, v140
	v_exp_f32_e32 v141, v141
	v_mul_f32_e32 v26, v134, v26
	v_mul_f32_e32 v27, v135, v27
	v_mul_f32_e32 v28, v136, v28
	v_mul_f32_e32 v29, v137, v29
	v_mul_f32_e32 v30, v138, v30
	v_mul_f32_e32 v31, v139, v31
	v_mul_f32_e32 v34, v140, v34
	v_mul_f32_e32 v35, v141, v35
	v_cvt_pk_bf16_f32 v18, v26, v27
	v_cvt_pk_bf16_f32 v19, v28, v29
	v_cvt_pk_bf16_f32 v20, v30, v31
	v_cvt_pk_bf16_f32 v21, v34, v35
	v_add3_u32 v22, v14, v24, v25
	ds_write_b128 v22, v[18:21]
	s_andn2_b64 exec, exec, s[6:7]
	s_cbranch_execnz .LBB0_309

; __device__ __forceinline__ float bf2f(bf16_t b) { return __uint_as_float((unsigned)b << 16); }
; __device__ __forceinline__ bf16_t f2bf(float f) { return (bf16_t)(pk2(f, 0.f) & 0xffffu); }
; __device__ __forceinline__ float fexp(float x) { return __expf(x); }
; __device__ __forceinline__ void gdn_unit(const Ctx& X, LAS unsigned char* hl, int b, int c, int h, int tid_h, int w4, int lane, int layer) {
;     ...
;     {
;         f32x4 acc[4];
;         const float eG63 = fexp(Gs[63]);
; #pragma unroll
;         for (int ct = 0; ct < 4; ++ct) acc[ct] = mma16(P, 16 * w4, WT, 16 * ct, (f32x4){0.f, 0.f, 0.f, 0.f}, r, q);
;         bf16_t* qe = WSP(bf16_t, WS_QEFF) + (size_t)uid * 4096;
; #pragma unroll
;         for (int ct = 0; ct < 4; ++ct)
; #pragma unroll
;             for (int j = 0; j < 4; ++j) { const int ii = 16 * w4 + 4 * q + j, col = 16 * ct + r;
;                 qe[ii * 64 + col] = f2bf(bf2f(Q[ii * LT + col]) * fexp(Gs[ii]) - acc[ct][j]); }
; #pragma unroll
;         for (int ct = 0; ct < 4; ++ct) acc[ct] = mma16(P, 16 * w4, UT, 16 * ct, (f32x4){0.f, 0.f, 0.f, 0.f}, r, q);
.LBB0_619:
	s_waitcnt lgkmcnt(0)
	s_barrier
	v_bfe_u32 v54, v224, 6, 2
	v_and_b32_e32 v55, 15, v232
	v_lshrrev_b32_e32 v56, 4, v232
	v_lshl_or_b32 v57, v54, 4, v55
	v_mul_u32_u24_e32 v58, 0x90, v57
	v_mul_u32_u24_e32 v59, 0x90, v55
	v_lshl_add_u32 v60, v56, 4, v58
	v_lshl_add_u32 v61, v56, 4, v59
	v_add_u32_e32 v60, v182, v60
	v_add_u32_e32 v61, v182, v61
	v_add_u32_e32 v178, 0xb400, v60
	v_add_u32_e32 v179, 0x4800, v61
	v_add_u32_e32 v60, 0x9000, v60
	v_add_u32_e32 v61, 0x6c00, v61
	ds_read_b128 v[6:9], v178
	ds_read_b128 v[10:13], v178 offset:64
	ds_read_b128 v[22:25], v179
	ds_read_b128 v[26:29], v179 offset:64
	ds_read_b128 v[30:33], v179 offset:2304
	ds_read_b128 v[34:37], v179 offset:2368
	ds_read_b128 v[38:41], v179 offset:4608
	ds_read_b128 v[42:45], v179 offset:4672
	ds_read_b128 v[46:49], v179 offset:6912
	ds_read_b128 v[50:53], v179 offset:6976
	ds_read_b128 v[14:17], v60
	ds_read_b128 v[18:21], v60 offset:64
	v_lshl_add_u32 v62, v57, 2, v185
	v_lshl_add_u32 v63, v56, 3, v58
	v_add_u32_e32 v63, v182, v63
	ds_read_b32 v176, v62
	ds_read_b32 v177, v185 offset:252
	s_lshl_b32 s0, s22, 9
	s_lshl_b32 s1, s23, 7
	s_add_i32 s1, s1, s0
	s_or_b32 s0, s1, s21
	s_ashr_i32 s1, s0, 31
	s_lshl_b64 s[0:1], s[0:1], 13
	s_add_u32 s4, s89, s0
	s_addc_u32 s5, s78, s1
	s_add_u32 s6, s79, s0
	s_addc_u32 s7, s80, s1
	v_readlane_b32 s98, v253, 3
	v_readlane_b32 s99, v253, 4
	s_add_u32 s98, s98, s0
	s_addc_u32 s99, s99, s1
	s_add_u32 s98, s98, 0xff000000
	s_addc_u32 s99, s99, -1
	s_add_u32 s100, s74, s0
	s_addc_u32 s101, s75, s1
	v_readfirstlane_b32 s32, v54
	v_lshlrev_b32_e32 v64, 11, v54
	v_lshlrev_b32_e32 v65, 5, v232
	v_lshl_add_u32 v64, v232, 4, v64
	v_lshlrev_b32_e32 v66, 9, v54
	v_lshl_add_u32 v66, v232, 3, v66
	v_add_u32_e32 v67, 0x1000, v66
	v_lshlrev_b32_e32 v71, 7, v57
	v_lshl_add_u32 v71, v56, 3, v71
	v_lshlrev_b32_e32 v70, 2, v56
	v_sub_u32_e32 v70, v55, v70
	s_waitcnt lgkmcnt(4)
	v_mfma_f32_16x16x32_bf16 v[134:137], v[22:25], v[6:9], 0
	v_mfma_f32_16x16x32_bf16 v[138:141], v[30:33], v[6:9], 0
	v_mfma_f32_16x16x32_bf16 v[142:145], v[38:41], v[6:9], 0
	v_mfma_f32_16x16x32_bf16 v[146:149], v[46:49], v[6:9], 0
	v_mfma_f32_16x16x32_bf16 v[134:137], v[26:29], v[10:13], v[134:137]
	v_mfma_f32_16x16x32_bf16 v[138:141], v[34:37], v[10:13], v[138:141]
	v_mfma_f32_16x16x32_bf16 v[142:145], v[42:45], v[10:13], v[142:145]
	v_mfma_f32_16x16x32_bf16 v[146:149], v[50:53], v[10:13], v[146:149]
	ds_read_b64 v[150:151], v63
	ds_read_b64 v[152:153], v63 offset:32
	ds_read_b64 v[172:173], v63 offset:64
	ds_read_b64 v[174:175], v63 offset:96
	ds_read_b128 v[186:189], v61
	ds_read_b128 v[190:193], v61 offset:64
	ds_read_b128 v[194:197], v61 offset:2304
	ds_read_b128 v[198:201], v61 offset:2368
	ds_read_b128 v[202:205], v61 offset:4608
	ds_read_b128 v[206:209], v61 offset:4672
	ds_read_b128 v[210:213], v61 offset:6912
	s_waitcnt lgkmcnt(13)
	v_mfma_f32_16x16x32_bf16 v[236:239], v[22:25], v[14:17], 0
	v_mfma_f32_16x16x32_bf16 v[240:243], v[30:33], v[14:17], 0
	v_mfma_f32_16x16x32_bf16 v[244:247], v[38:41], v[14:17], 0
	v_mfma_f32_16x16x32_bf16 v[248:251], v[46:49], v[14:17], 0
	v_mfma_f32_16x16x32_bf16 v[236:239], v[26:29], v[18:21], v[236:239]
	v_mfma_f32_16x16x32_bf16 v[240:243], v[34:37], v[18:21], v[240:243]
	v_mfma_f32_16x16x32_bf16 v[244:247], v[42:45], v[18:21], v[244:247]
	v_mfma_f32_16x16x32_bf16 v[248:251], v[50:53], v[18:21], v[248:251]
	ds_read_b128 v[214:217], v61 offset:6976
	s_waitcnt lgkmcnt(8)
	v_mul_f32_e32 v176, 0x3fb8aa3b, v176
	v_mul_f32_e32 v177, 0x3fb8aa3b, v177
	v_exp_f32_e32 v176, v176
	v_exp_f32_e32 v177, v177
	v_cmp_eq_u32_e32 vcc, 0, v70
	v_cmp_eq_u32_e64 s[0:1], 1, v70
	v_lshlrev_b32_e32 v76, 16, v150
	v_and_b32_e32 v77, 0xffff0000, v150
	v_cndmask_b32_e32 v72, 0, v177, vcc
	v_cndmask_b32_e64 v73, 0, v177, s[0:1]
	v_cmp_eq_u32_e32 vcc, 2, v70
	v_cmp_eq_u32_e64 s[0:1], 3, v70
	v_lshlrev_b32_e32 v78, 16, v151
	v_and_b32_e32 v79, 0xffff0000, v151
	v_cndmask_b32_e32 v74, 0, v177, vcc
	v_cndmask_b32_e64 v75, 0, v177, s[0:1]
	s_waitcnt lgkmcnt(0)
; __device__ __forceinline__ float bf2f(bf16_t b) { return __uint_as_float((unsigned)b << 16); }
; __device__ __forceinline__ bf16_t f2bf(float f) { return (bf16_t)(pk2(f, 0.f) & 0xffffu); }
; __device__ __forceinline__ float fexp(float x) { return __expf(x); }
; __device__ __forceinline__ void gdn_unit(const Ctx& X, LAS unsigned char* hl, int b, int c, int h, int tid_h, int w4, int lane, int layer) {
;     ...
;         bf16_t* qe = WSP(bf16_t, WS_QEFF) + (size_t)uid * 4096;
; #pragma unroll
;         for (int ct = 0; ct < 4; ++ct)
; #pragma unroll
;             for (int j = 0; j < 4; ++j) { const int ii = 16 * w4 + 4 * q + j, col = 16 * ct + r;
;                 qe[ii * 64 + col] = f2bf(bf2f(Q[ii * LT + col]) * fexp(Gs[ii]) - acc[ct][j]); }
; #pragma unroll
;         for (int ct = 0; ct < 4; ++ct) acc[ct] = mma16(P, 16 * w4, UT, 16 * ct, (f32x4){0.f, 0.f, 0.f, 0.f}, r, q);
;         store_oloc(WSP(bf16_t, WS_OLOC), uid, w4, lane, acc);
; #pragma unroll
;         for (int ct = 0; ct < 4; ++ct) acc[ct] = mma16(KDT, 16 * w4, WT, 16 * ct, (f32x4){0.f, 0.f, 0.f, 0.f}, r, q);
;         bf16_t* mm = WSP(bf16_t, WS_MM) + (size_t)(uid - 2048) * 4096;
; #pragma unroll
;         for (int ct = 0; ct < 4; ++ct)
; #pragma unroll
;             for (int j = 0; j < 4; ++j) { const int ii = 16 * w4 + 4 * q + j, col = 16 * ct + r;
;                 mm[((w4 * 2 + (ct >> 1)) * 64 + (r >> 2) * 16 + 4 * q + j) * 8 + (ct & 1) * 4 + (r & 3)] = f2bf((ii == col ? eG63 : 0.f) - acc[ct][j]); }
; #pragma unroll
;         for (int ct = 0; ct < 4; ++ct) acc[ct] = mma16(KDT, 16 * w4, UT, 16 * ct, (f32x4){0.f, 0.f, 0.f, 0.f}, r, q);
;         store_bc(WSP(bf16_t, WS_BCS), uid, w4, r, q, acc);
;     }
	v_mfma_f32_16x16x32_bf16 v[84:87], v[6:9], v[186:189], 0
	v_mfma_f32_16x16x32_bf16 v[88:91], v[6:9], v[194:197], 0
	v_mfma_f32_16x16x32_bf16 v[92:95], v[6:9], v[202:205], 0
	v_mfma_f32_16x16x32_bf16 v[96:99], v[6:9], v[210:213], 0
	v_mfma_f32_16x16x32_bf16 v[114:117], v[14:17], v[186:189], 0
	v_mfma_f32_16x16x32_bf16 v[118:121], v[14:17], v[194:197], 0
	v_mfma_f32_16x16x32_bf16 v[122:125], v[14:17], v[202:205], 0
	v_mfma_f32_16x16x32_bf16 v[126:129], v[14:17], v[210:213], 0
	v_mfma_f32_16x16x32_bf16 v[84:87], v[10:13], v[190:193], v[84:87]
	v_mfma_f32_16x16x32_bf16 v[88:91], v[10:13], v[198:201], v[88:91]
	v_mfma_f32_16x16x32_bf16 v[92:95], v[10:13], v[206:209], v[92:95]
	v_mfma_f32_16x16x32_bf16 v[96:99], v[10:13], v[214:217], v[96:99]
	v_mfma_f32_16x16x32_bf16 v[114:117], v[18:21], v[190:193], v[114:117]
	v_mfma_f32_16x16x32_bf16 v[118:121], v[18:21], v[198:201], v[118:121]
	v_mfma_f32_16x16x32_bf16 v[122:125], v[18:21], v[206:209], v[122:125]
	v_mfma_f32_16x16x32_bf16 v[126:129], v[18:21], v[214:217], v[126:129]
	v_fma_f32 v76, v176, v76, -v134
	v_fma_f32 v77, v176, v77, -v135
	v_fma_f32 v78, v176, v78, -v136
	v_fma_f32 v79, v176, v79, -v137
	v_cvt_pk_bf16_f32 v218, v76, v77
	v_cvt_pk_bf16_f32 v219, v78, v79
	global_store_dwordx2 v71, v[218:219], s[4:5]
	v_lshlrev_b32_e32 v76, 16, v152
	v_and_b32_e32 v77, 0xffff0000, v152
	v_lshlrev_b32_e32 v78, 16, v153
	v_and_b32_e32 v79, 0xffff0000, v153
	v_fma_f32 v76, v176, v76, -v138
	v_fma_f32 v77, v176, v77, -v139
	v_fma_f32 v78, v176, v78, -v140
	v_fma_f32 v79, v176, v79, -v141
	v_cvt_pk_bf16_f32 v220, v76, v77
	v_cvt_pk_bf16_f32 v221, v78, v79
	global_store_dwordx2 v71, v[220:221], s[4:5] offset:32
	v_lshlrev_b32_e32 v76, 16, v172
	v_and_b32_e32 v77, 0xffff0000, v172
	v_lshlrev_b32_e32 v78, 16, v173
	v_and_b32_e32 v79, 0xffff0000, v173
	v_fma_f32 v76, v176, v76, -v142
	v_fma_f32 v77, v176, v77, -v143
	v_fma_f32 v78, v176, v78, -v144
	v_fma_f32 v79, v176, v79, -v145
	v_cvt_pk_bf16_f32 v222, v76, v77
	v_cvt_pk_bf16_f32 v223, v78, v79
	global_store_dwordx2 v71, v[222:223], s[4:5] offset:64
	v_lshlrev_b32_e32 v76, 16, v174
	v_and_b32_e32 v77, 0xffff0000, v174
	v_lshlrev_b32_e32 v78, 16, v175
	v_and_b32_e32 v79, 0xffff0000, v175
	v_fma_f32 v76, v176, v76, -v146
	v_fma_f32 v77, v176, v77, -v147
	v_fma_f32 v78, v176, v78, -v148
	v_fma_f32 v79, v176, v79, -v149
	v_cvt_pk_bf16_f32 v226, v76, v77
	v_cvt_pk_bf16_f32 v227, v78, v79
	global_store_dwordx2 v71, v[226:227], s[4:5] offset:96
	s_cmp_eq_u32 s32, 0
	s_cselect_b32 s0, 1.0, 0
	v_fma_f32 v76, v72, s0, -v236
	v_fma_f32 v77, v73, s0, -v237
	v_fma_f32 v78, v74, s0, -v238
	v_fma_f32 v79, v75, s0, -v239
	v_cvt_pk_bf16_f32 v100, v76, v77
	v_cvt_pk_bf16_f32 v101, v78, v79
	s_cmp_eq_u32 s32, 1
	s_cselect_b32 s0, 1.0, 0
	v_fma_f32 v76, v72, s0, -v240
	v_fma_f32 v77, v73, s0, -v241
	v_fma_f32 v78, v74, s0, -v242
	v_fma_f32 v79, v75, s0, -v243
	v_cvt_pk_bf16_f32 v102, v76, v77
	v_cvt_pk_bf16_f32 v103, v78, v79
	global_store_dwordx4 v64, v[100:103], s[98:99]
	s_cmp_eq_u32 s32, 2
	s_cselect_b32 s0, 1.0, 0
	v_fma_f32 v76, v72, s0, -v244
	v_fma_f32 v77, v73, s0, -v245
	v_fma_f32 v78, v74, s0, -v246
	v_fma_f32 v79, v75, s0, -v247
	v_cvt_pk_bf16_f32 v104, v76, v77
	v_cvt_pk_bf16_f32 v105, v78, v79
	s_cmp_eq_u32 s32, 3
	s_cselect_b32 s0, 1.0, 0
	v_fma_f32 v76, v72, s0, -v248
	v_fma_f32 v77, v73, s0, -v249
	v_fma_f32 v78, v74, s0, -v250
	v_fma_f32 v79, v75, s0, -v251
	v_cvt_pk_bf16_f32 v106, v76, v77
	v_cvt_pk_bf16_f32 v107, v78, v79
	global_store_dwordx4 v64, v[104:107], s[98:99] offset:1024
	v_cvt_pk_bf16_f32 v108, v84, v85
	v_cvt_pk_bf16_f32 v109, v86, v87
	v_cvt_pk_bf16_f32 v110, v88, v89
	v_cvt_pk_bf16_f32 v111, v90, v91
	global_store_dwordx4 v65, v[108:111], s[6:7] nt
	v_cvt_pk_bf16_f32 v80, v92, v93
	v_cvt_pk_bf16_f32 v81, v94, v95
	v_cvt_pk_bf16_f32 v82, v96, v97
	v_cvt_pk_bf16_f32 v83, v98, v99
	global_store_dwordx4 v65, v[80:83], s[6:7] offset:16 nt
	v_cvt_pk_bf16_f32 v40, v114, v115
	v_cvt_pk_bf16_f32 v41, v116, v117
	global_store_dwordx2 v66, v[40:41], s[100:101]
	v_cvt_pk_bf16_f32 v42, v118, v119
	v_cvt_pk_bf16_f32 v43, v120, v121
	global_store_dwordx2 v66, v[42:43], s[100:101] offset:2048
	v_cvt_pk_bf16_f32 v44, v122, v123
	v_cvt_pk_bf16_f32 v45, v124, v125
	global_store_dwordx2 v67, v[44:45], s[100:101]
	v_cvt_pk_bf16_f32 v46, v126, v127
	v_cvt_pk_bf16_f32 v47, v128, v129
	global_store_dwordx2 v67, v[46:47], s[100:101] offset:2048
	s_branch .Lgdn_p4_pad_end
	s_nop 0
	s_nop 0
	s_nop 0
	s_nop 0
	s_nop 0
	s_nop 0
	s_nop 0
	s_nop 0
	s_nop 0
	s_nop 0
	s_nop 0
	s_nop 0
	s_nop 0
	s_nop 0
	s_nop 0
	s_nop 0
	s_nop 0
	s_nop 0
	s_nop 0
	s_nop 0
	s_nop 0
	s_nop 0
	s_nop 0
	s_nop 0
	s_nop 0
	s_nop 0
	s_nop 0
	s_nop 0
	s_nop 0
	s_nop 0
	s_nop 0
	s_nop 0
	s_nop 0
	s_nop 0
	s_nop 0
	s_nop 0
	s_nop 0
	s_nop 0
	s_nop 0
	s_nop 0
	s_nop 0
	s_nop 0
	s_nop 0
	s_nop 0
	s_nop 0
	s_nop 0
	s_nop 0
	s_nop 0
	s_nop 0
	s_nop 0
	s_nop 0
	s_nop 0
	s_nop 0
	s_nop 0
	s_nop 0
	s_nop 0
	s_nop 0
	s_nop 0
	s_nop 0
	s_nop 0
	s_nop 0
	s_nop 0
	s_nop 0
	s_nop 0
	s_nop 0
	s_nop 0
	s_nop 0
	s_nop 0
	s_nop 0
	s_nop 0
	s_nop 0
	s_nop 0
	s_nop 0
	s_nop 0
	s_nop 0
	s_nop 0
	s_nop 0
	s_nop 0
	s_nop 0
	s_nop 0
	s_nop 0
	s_nop 0
	s_nop 0
	s_nop 0
	s_nop 0
	s_nop 0
	s_nop 0
	s_nop 0
	s_nop 0
	s_nop 0
	s_nop 0
	s_nop 0
	s_nop 0
	s_nop 0
	s_nop 0
	s_nop 0
	s_nop 0
	s_nop 0
	s_nop 0
	s_nop 0
	s_nop 0
	s_nop 0
	s_nop 0
	s_nop 0
	s_nop 0
	s_nop 0
	s_nop 0
	s_nop 0
	s_nop 0
	s_nop 0
	s_nop 0
	s_nop 0
	s_nop 0
	s_nop 0
	s_nop 0
	s_nop 0
	s_nop 0
	s_nop 0
	s_nop 0
	s_nop 0
	s_nop 0
	s_nop 0
	s_nop 0
	s_nop 0
	s_nop 0
	s_nop 0
	s_nop 0
	s_nop 0
	s_nop 0
	s_nop 0
	s_nop 0
	s_nop 0
	s_nop 0
	s_nop 0
	s_nop 0
	s_nop 0
	s_nop 0
	s_nop 0
	s_nop 0
	s_nop 0
	s_nop 0
	s_nop 0
	s_nop 0
	s_nop 0
	s_nop 0
	s_nop 0
	s_nop 0
	s_nop 0
	s_nop 0
	s_nop 0
	s_nop 0
	s_nop 0
	s_nop 0
	s_nop 0
	s_nop 0
	s_nop 0
	s_nop 0
	s_nop 0
	s_nop 0
	s_nop 0
	s_nop 0
	s_nop 0
	s_nop 0
	s_nop 0
	s_nop 0
	s_nop 0
	s_nop 0
	s_nop 0
	s_nop 0
	s_nop 0
	s_nop 0
	s_nop 0
	s_nop 0
	s_nop 0
	s_nop 0
	s_nop 0
	s_nop 0
	s_nop 0
	s_nop 0
	s_nop 0
	s_nop 0
	s_nop 0
	s_nop 0
	s_nop 0
	s_nop 0
	s_nop 0
	s_nop 0
	s_nop 0
	s_nop 0
	s_nop 0
	s_nop 0
	s_nop 0
	s_nop 0
	s_nop 0
	s_nop 0
	s_nop 0
	s_nop 0
	s_nop 0
	s_nop 0
	s_nop 0
	s_nop 0
	s_nop 0
	s_nop 0
	s_nop 0
	s_nop 0
	s_nop 0
	s_nop 0
	s_nop 0
	s_nop 0
	s_nop 0
	s_nop 0
	s_nop 0
	s_nop 0
	s_nop 0
	s_nop 0
	s_nop 0
	s_nop 0
	s_nop 0
	s_nop 0
	s_nop 0
	s_nop 0
	s_nop 0
	s_nop 0
	s_nop 0
	s_nop 0
	s_nop 0
	s_nop 0
	s_nop 0
	s_nop 0
	s_nop 0
	s_nop 0
	s_nop 0
	s_nop 0
	s_nop 0
	s_nop 0
	s_nop 0
	s_nop 0
	s_nop 0
	s_nop 0
	s_nop 0
	s_nop 0
	s_nop 0
	s_nop 0
	s_nop 0
	s_nop 0
	s_nop 0
	s_nop 0
	s_nop 0
	s_nop 0
	s_nop 0
	s_nop 0
	s_nop 0
	s_nop 0
	s_nop 0
	s_nop 0
	s_nop 0
	s_nop 0
	s_nop 0
	s_nop 0
	s_nop 0
	s_nop 0
	s_nop 0
